# residual-update GEMM epilogues (FFN-down x2, w_out): X loads prefetched one row ahead with counted waits instead of 32 serialized load/store chains
# speedup vs baseline: 1.0563x; 1.0039x over previous
.LBB0_313:
	v_and_b32_e32 v140, 64, v197
	v_xor_b32_e32 v139, 16, v197
	v_add_u32_e32 v140, 64, v140
	v_cmp_lt_i32_e32 vcc, v139, v140
	v_lshl_add_u32 v138, s46, 8, v142
	v_lshl_or_b32 v136, s45, 8, v144
	v_cndmask_b32_e32 v139, v197, v139, vcc
	v_lshlrev_b32_e32 v162, 2, v139
	v_xor_b32_e32 v139, 32, v197
	v_cmp_lt_i32_e32 vcc, v139, v140
	v_ashrrev_i32_e32 v137, 31, v136
	s_lshl_b32 s20, s45, 2
	v_cndmask_b32_e32 v139, v197, v139, vcc
	v_lshlrev_b32_e32 v160, 2, v139
	v_ashrrev_i32_e32 v139, 31, v138
	v_lshlrev_b64 v[140:141], 10, v[138:139]
	v_lshl_add_u64 v[168:169], v[140:141], 0, v[136:137]
	v_lshl_add_u64 v[140:141], v[168:169], 2, s[4:5]
	v_mov_b64_e32 v[204:205], v[140:141]
	global_load_dwordx4 v[208:211], v[204:205], off
	global_load_dwordx4 v[212:215], v[204:205], off offset:64
	global_load_dwordx4 v[216:219], v[204:205], off offset:512
	global_load_dwordx4 v[220:223], v[204:205], off offset:576
	s_mov_b64 s[22:23], 0x10000
	v_lshl_add_u64 v[206:207], v[204:205], 0, s[22:23]
	global_load_dwordx4 v[224:227], v[206:207], off
	global_load_dwordx4 v[228:231], v[206:207], off offset:64
	global_load_dwordx4 v[232:235], v[206:207], off offset:512
	global_load_dwordx4 v[236:239], v[206:207], off offset:576
	s_ashr_i32 s21, s20, 31
	s_waitcnt vmcnt(7)
	v_mov_b64_e32 v[164:165], v[208:209]
	v_mov_b64_e32 v[166:167], v[210:211]
	v_pk_fma_f32 v[166:167], v[128:129], 0.5, v[166:167] op_sel_hi:[1,0,1]
	v_pk_fma_f32 v[164:165], v[126:127], 0.5, v[164:165] op_sel_hi:[1,0,1]
	v_lshlrev_b64 v[126:127], 1, v[168:169]
	v_cvt_pk_bf16_f32 v128, v164, v165
	v_cvt_pk_bf16_f32 v129, v166, v167
	v_lshl_add_u64 v[168:169], s[14:15], 0, v[126:127]
	global_store_dwordx4 v[140:141], v[164:167], off
	global_store_dwordx2 v[168:169], v[128:129], off
	v_mul_f32_e32 v128, v165, v165
	v_mul_f32_e32 v129, v167, v167
	v_fmac_f32_e32 v128, v164, v164
	v_fmac_f32_e32 v129, v166, v166
	v_add_f32_e32 v163, v128, v129
	s_waitcnt vmcnt(8)
	v_mov_b64_e32 v[164:165], v[212:213]
	v_mov_b64_e32 v[166:167], v[214:215]
	v_pk_fma_f32 v[124:125], v[124:125], 0.5, v[166:167] op_sel_hi:[1,0,1]
	v_pk_fma_f32 v[122:123], v[122:123], 0.5, v[164:165] op_sel_hi:[1,0,1]
	global_store_dwordx4 v[140:141], v[122:125], off offset:64
	v_cvt_pk_bf16_f32 v128, v122, v123
	v_or_b32_e32 v164, 32, v126
	v_mul_f32_e32 v123, v123, v123
	v_mov_b32_e32 v165, v127
	v_fmac_f32_e32 v123, v122, v122
	v_mul_f32_e32 v122, v125, v125
	v_cvt_pk_bf16_f32 v129, v124, v125
	v_lshl_add_u64 v[164:165], s[14:15], 0, v[164:165]
	v_fmac_f32_e32 v122, v124, v124
	global_store_dwordx2 v[164:165], v[128:129], off
	v_add_f32_e32 v122, v123, v122
	v_add_f32_e32 v128, v163, v122
	s_waitcnt vmcnt(9)
	v_mov_b64_e32 v[122:123], v[216:217]
	v_mov_b64_e32 v[124:125], v[218:219]
	v_pk_fma_f32 v[120:121], v[120:121], 0.5, v[124:125] op_sel_hi:[1,0,1]
	v_pk_fma_f32 v[118:119], v[118:119], 0.5, v[122:123] op_sel_hi:[1,0,1]
	global_store_dwordx4 v[140:141], v[118:121], off offset:512
	v_cvt_pk_bf16_f32 v122, v118, v119
	v_or_b32_e32 v124, 0x100, v126
	v_mul_f32_e32 v119, v119, v119
	v_mov_b32_e32 v125, v127
	v_fmac_f32_e32 v119, v118, v118
	v_mul_f32_e32 v118, v121, v121
	v_cvt_pk_bf16_f32 v123, v120, v121
	v_lshl_add_u64 v[124:125], s[14:15], 0, v[124:125]
	v_fmac_f32_e32 v118, v120, v120
	global_store_dwordx2 v[124:125], v[122:123], off
	v_add_f32_e32 v118, v119, v118
	v_add_f32_e32 v122, v128, v118
	v_or_b32_e32 v126, 0x120, v126
	s_waitcnt vmcnt(10)
	v_mov_b64_e32 v[118:119], v[220:221]
	v_mov_b64_e32 v[120:121], v[222:223]
	v_pk_fma_f32 v[116:117], v[116:117], 0.5, v[120:121] op_sel_hi:[1,0,1]
	v_pk_fma_f32 v[114:115], v[114:115], 0.5, v[118:119] op_sel_hi:[1,0,1]
	global_store_dwordx4 v[140:141], v[114:117], off offset:576
	v_cvt_pk_bf16_f32 v118, v114, v115
	v_cvt_pk_bf16_f32 v119, v116, v117
	v_mul_f32_e32 v115, v115, v115
	v_fmac_f32_e32 v115, v114, v114
	v_mul_f32_e32 v114, v117, v117
	v_fmac_f32_e32 v114, v116, v116
	v_add_f32_e32 v114, v115, v114
	v_add_f32_e32 v114, v122, v114
	ds_bpermute_b32 v115, v162, v114
	v_lshl_add_u64 v[120:121], s[14:15], 0, v[126:127]
	global_store_dwordx2 v[120:121], v[118:119], off
	s_waitcnt lgkmcnt(0)
	v_add_f32_e32 v114, v114, v115
	ds_bpermute_b32 v115, v160, v114
	s_and_saveexec_b64 s[22:23], s[8:9]
	s_cbranch_execz .LBB0_315
	v_lshlrev_b64 v[116:117], 6, v[138:139]
	v_lshl_add_u64 v[116:117], s[66:67], 0, v[116:117]
	v_lshl_add_u64 v[116:117], s[20:21], 2, v[116:117]
	s_lshl_b32 s68, s39, 2
	v_lshl_add_u64 v[116:117], v[116:117], 0, s[68:69]
	s_waitcnt lgkmcnt(0)
	v_add_f32_e32 v114, v114, v115
	global_store_dword v[116:117], v114, off
.LBB0_315:
	s_or_b64 exec, exec, s[22:23]
	v_or_b32_e32 v114, 16, v138
	s_waitcnt lgkmcnt(0)
	v_ashrrev_i32_e32 v115, 31, v114
	v_lshlrev_b64 v[116:117], 10, v[114:115]
	v_lshl_add_u64 v[122:123], v[116:117], 0, v[136:137]
	v_lshl_add_u64 v[116:117], v[122:123], 2, s[4:5]
	s_mov_b64 s[22:23], 0x20000
	v_lshl_add_u64 v[206:207], v[204:205], 0, s[22:23]
	global_load_dwordx4 v[208:211], v[206:207], off
	global_load_dwordx4 v[212:215], v[206:207], off offset:64
	global_load_dwordx4 v[216:219], v[206:207], off offset:512
	global_load_dwordx4 v[220:223], v[206:207], off offset:576
	s_waitcnt vmcnt(16)
	v_mov_b64_e32 v[118:119], v[224:225]
	v_mov_b64_e32 v[120:121], v[226:227]
	v_pk_fma_f32 v[120:121], v[112:113], 0.5, v[120:121] op_sel_hi:[1,0,1]
	v_pk_fma_f32 v[118:119], v[110:111], 0.5, v[118:119] op_sel_hi:[1,0,1]
	v_lshlrev_b64 v[110:111], 1, v[122:123]
	v_cvt_pk_bf16_f32 v112, v118, v119
	v_cvt_pk_bf16_f32 v113, v120, v121
	v_lshl_add_u64 v[122:123], s[14:15], 0, v[110:111]
	global_store_dwordx4 v[116:117], v[118:121], off
	global_store_dwordx2 v[122:123], v[112:113], off
	v_mul_f32_e32 v112, v119, v119
	v_mul_f32_e32 v113, v121, v121
	v_fmac_f32_e32 v112, v118, v118
	v_fmac_f32_e32 v113, v120, v120
	v_add_f32_e32 v122, v112, v113
	s_waitcnt vmcnt(17)
	v_mov_b64_e32 v[118:119], v[228:229]
	v_mov_b64_e32 v[120:121], v[230:231]
	v_pk_fma_f32 v[108:109], v[108:109], 0.5, v[120:121] op_sel_hi:[1,0,1]
	v_pk_fma_f32 v[106:107], v[106:107], 0.5, v[118:119] op_sel_hi:[1,0,1]
	global_store_dwordx4 v[116:117], v[106:109], off offset:64
	v_cvt_pk_bf16_f32 v112, v106, v107
	v_or_b32_e32 v118, 32, v110
	v_mul_f32_e32 v107, v107, v107
	v_mov_b32_e32 v119, v111
	v_fmac_f32_e32 v107, v106, v106
	v_mul_f32_e32 v106, v109, v109
	v_cvt_pk_bf16_f32 v113, v108, v109
	v_lshl_add_u64 v[118:119], s[14:15], 0, v[118:119]
	v_fmac_f32_e32 v106, v108, v108
	global_store_dwordx2 v[118:119], v[112:113], off
	v_add_f32_e32 v106, v107, v106
	v_add_f32_e32 v112, v122, v106
	s_waitcnt vmcnt(18)
	v_mov_b64_e32 v[106:107], v[232:233]
	v_mov_b64_e32 v[108:109], v[234:235]
	v_pk_fma_f32 v[104:105], v[104:105], 0.5, v[108:109] op_sel_hi:[1,0,1]
	v_pk_fma_f32 v[102:103], v[102:103], 0.5, v[106:107] op_sel_hi:[1,0,1]
	global_store_dwordx4 v[116:117], v[102:105], off offset:512
	v_cvt_pk_bf16_f32 v106, v102, v103
	v_or_b32_e32 v108, 0x100, v110
	v_mul_f32_e32 v103, v103, v103
	v_mov_b32_e32 v109, v111
	v_fmac_f32_e32 v103, v102, v102
	v_mul_f32_e32 v102, v105, v105
	v_cvt_pk_bf16_f32 v107, v104, v105
	v_lshl_add_u64 v[108:109], s[14:15], 0, v[108:109]
	v_fmac_f32_e32 v102, v104, v104
	global_store_dwordx2 v[108:109], v[106:107], off
	v_add_f32_e32 v102, v103, v102
	v_add_f32_e32 v106, v112, v102
	v_or_b32_e32 v110, 0x120, v110
	s_waitcnt vmcnt(19)
	v_mov_b64_e32 v[102:103], v[236:237]
	v_mov_b64_e32 v[104:105], v[238:239]
	v_pk_fma_f32 v[100:101], v[100:101], 0.5, v[104:105] op_sel_hi:[1,0,1]
	v_pk_fma_f32 v[98:99], v[98:99], 0.5, v[102:103] op_sel_hi:[1,0,1]
	global_store_dwordx4 v[116:117], v[98:101], off offset:576
	v_cvt_pk_bf16_f32 v102, v98, v99
	v_cvt_pk_bf16_f32 v103, v100, v101
	v_mul_f32_e32 v99, v99, v99
	v_fmac_f32_e32 v99, v98, v98
	v_mul_f32_e32 v98, v101, v101
	v_fmac_f32_e32 v98, v100, v100
	v_add_f32_e32 v98, v99, v98
	v_add_f32_e32 v98, v106, v98
	ds_bpermute_b32 v99, v162, v98
	v_lshl_add_u64 v[104:105], s[14:15], 0, v[110:111]
	global_store_dwordx2 v[104:105], v[102:103], off
	s_waitcnt lgkmcnt(0)
	v_add_f32_e32 v98, v98, v99
	ds_bpermute_b32 v99, v160, v98
	s_and_saveexec_b64 s[22:23], s[8:9]
	s_cbranch_execz .LBB0_317
	v_lshlrev_b64 v[100:101], 6, v[114:115]
	v_lshl_add_u64 v[100:101], s[66:67], 0, v[100:101]
	v_lshl_add_u64 v[100:101], s[20:21], 2, v[100:101]
	s_lshl_b32 s68, s39, 2
	v_lshl_add_u64 v[100:101], v[100:101], 0, s[68:69]
	s_waitcnt lgkmcnt(0)
	v_add_f32_e32 v98, v98, v99
	global_store_dword v[100:101], v98, off
.LBB0_317:
	s_or_b64 exec, exec, s[22:23]
	v_or_b32_e32 v98, 32, v138
	s_waitcnt lgkmcnt(0)
	v_ashrrev_i32_e32 v99, 31, v98
	v_lshlrev_b64 v[100:101], 10, v[98:99]
	v_lshl_add_u64 v[106:107], v[100:101], 0, v[136:137]
	v_lshl_add_u64 v[100:101], v[106:107], 2, s[4:5]
	s_mov_b64 s[22:23], 0x30000
	v_lshl_add_u64 v[206:207], v[204:205], 0, s[22:23]
	global_load_dwordx4 v[224:227], v[206:207], off
	global_load_dwordx4 v[228:231], v[206:207], off offset:64
	global_load_dwordx4 v[232:235], v[206:207], off offset:512
	global_load_dwordx4 v[236:239], v[206:207], off offset:576
	s_waitcnt vmcnt(16)
	v_mov_b64_e32 v[102:103], v[208:209]
	v_mov_b64_e32 v[104:105], v[210:211]
	v_pk_fma_f32 v[104:105], v[96:97], 0.5, v[104:105] op_sel_hi:[1,0,1]
	v_pk_fma_f32 v[102:103], v[94:95], 0.5, v[102:103] op_sel_hi:[1,0,1]
	v_lshlrev_b64 v[94:95], 1, v[106:107]
	v_cvt_pk_bf16_f32 v96, v102, v103
	v_cvt_pk_bf16_f32 v97, v104, v105
	v_lshl_add_u64 v[106:107], s[14:15], 0, v[94:95]
	global_store_dwordx4 v[100:101], v[102:105], off
	global_store_dwordx2 v[106:107], v[96:97], off
	v_mul_f32_e32 v96, v103, v103
	v_mul_f32_e32 v97, v105, v105
	v_fmac_f32_e32 v96, v102, v102
	v_fmac_f32_e32 v97, v104, v104
	v_add_f32_e32 v106, v96, v97
	s_waitcnt vmcnt(17)
	v_mov_b64_e32 v[102:103], v[212:213]
	v_mov_b64_e32 v[104:105], v[214:215]
	v_pk_fma_f32 v[92:93], v[92:93], 0.5, v[104:105] op_sel_hi:[1,0,1]
	v_pk_fma_f32 v[90:91], v[90:91], 0.5, v[102:103] op_sel_hi:[1,0,1]
	global_store_dwordx4 v[100:101], v[90:93], off offset:64
	v_cvt_pk_bf16_f32 v96, v90, v91
	v_or_b32_e32 v102, 32, v94
	v_mul_f32_e32 v91, v91, v91
	v_mov_b32_e32 v103, v95
	v_fmac_f32_e32 v91, v90, v90
	v_mul_f32_e32 v90, v93, v93
	v_cvt_pk_bf16_f32 v97, v92, v93
	v_lshl_add_u64 v[102:103], s[14:15], 0, v[102:103]
	v_fmac_f32_e32 v90, v92, v92
	global_store_dwordx2 v[102:103], v[96:97], off
	v_add_f32_e32 v90, v91, v90
	v_add_f32_e32 v96, v106, v90
	s_waitcnt vmcnt(18)
	v_mov_b64_e32 v[90:91], v[216:217]
	v_mov_b64_e32 v[92:93], v[218:219]
	v_pk_fma_f32 v[88:89], v[88:89], 0.5, v[92:93] op_sel_hi:[1,0,1]
	v_pk_fma_f32 v[86:87], v[86:87], 0.5, v[90:91] op_sel_hi:[1,0,1]
	global_store_dwordx4 v[100:101], v[86:89], off offset:512
	v_cvt_pk_bf16_f32 v90, v86, v87
	v_or_b32_e32 v92, 0x100, v94
	v_mul_f32_e32 v87, v87, v87
	v_mov_b32_e32 v93, v95
	v_fmac_f32_e32 v87, v86, v86
	v_mul_f32_e32 v86, v89, v89
	v_cvt_pk_bf16_f32 v91, v88, v89
	v_lshl_add_u64 v[92:93], s[14:15], 0, v[92:93]
	v_fmac_f32_e32 v86, v88, v88
	global_store_dwordx2 v[92:93], v[90:91], off
	v_add_f32_e32 v86, v87, v86
	v_add_f32_e32 v90, v96, v86
	v_or_b32_e32 v94, 0x120, v94
	s_waitcnt vmcnt(19)
	v_mov_b64_e32 v[86:87], v[220:221]
	v_mov_b64_e32 v[88:89], v[222:223]
	v_pk_fma_f32 v[84:85], v[84:85], 0.5, v[88:89] op_sel_hi:[1,0,1]
	v_pk_fma_f32 v[82:83], v[82:83], 0.5, v[86:87] op_sel_hi:[1,0,1]
	global_store_dwordx4 v[100:101], v[82:85], off offset:576
	v_cvt_pk_bf16_f32 v86, v82, v83
	v_cvt_pk_bf16_f32 v87, v84, v85
	v_mul_f32_e32 v83, v83, v83
	v_fmac_f32_e32 v83, v82, v82
	v_mul_f32_e32 v82, v85, v85
	v_fmac_f32_e32 v82, v84, v84
	v_add_f32_e32 v82, v83, v82
	v_add_f32_e32 v82, v90, v82
	ds_bpermute_b32 v83, v162, v82
	v_lshl_add_u64 v[88:89], s[14:15], 0, v[94:95]
	global_store_dwordx2 v[88:89], v[86:87], off
	s_waitcnt lgkmcnt(0)
	v_add_f32_e32 v82, v82, v83
	ds_bpermute_b32 v83, v160, v82
	s_and_saveexec_b64 s[22:23], s[8:9]
	s_cbranch_execz .LBB0_319
	v_lshlrev_b64 v[84:85], 6, v[98:99]
	v_lshl_add_u64 v[84:85], s[66:67], 0, v[84:85]
	v_lshl_add_u64 v[84:85], s[20:21], 2, v[84:85]
	s_lshl_b32 s68, s39, 2
	v_lshl_add_u64 v[84:85], v[84:85], 0, s[68:69]
	s_waitcnt lgkmcnt(0)
	v_add_f32_e32 v82, v82, v83
	global_store_dword v[84:85], v82, off
.LBB0_319:
	s_or_b64 exec, exec, s[22:23]
	v_or_b32_e32 v82, 48, v138
	s_waitcnt lgkmcnt(0)
	v_ashrrev_i32_e32 v83, 31, v82
	v_lshlrev_b64 v[84:85], 10, v[82:83]
	v_lshl_add_u64 v[90:91], v[84:85], 0, v[136:137]
	v_lshl_add_u64 v[84:85], v[90:91], 2, s[4:5]
	s_mov_b64 s[22:23], 0x80000
	v_lshl_add_u64 v[206:207], v[204:205], 0, s[22:23]
	global_load_dwordx4 v[208:211], v[206:207], off
	global_load_dwordx4 v[212:215], v[206:207], off offset:64
	global_load_dwordx4 v[216:219], v[206:207], off offset:512
	global_load_dwordx4 v[220:223], v[206:207], off offset:576
	s_waitcnt vmcnt(16)
	v_mov_b64_e32 v[86:87], v[224:225]
	v_mov_b64_e32 v[88:89], v[226:227]
	v_pk_fma_f32 v[88:89], v[80:81], 0.5, v[88:89] op_sel_hi:[1,0,1]
	v_pk_fma_f32 v[86:87], v[78:79], 0.5, v[86:87] op_sel_hi:[1,0,1]
	v_lshlrev_b64 v[78:79], 1, v[90:91]
	v_cvt_pk_bf16_f32 v80, v86, v87
	v_cvt_pk_bf16_f32 v81, v88, v89
	v_lshl_add_u64 v[90:91], s[14:15], 0, v[78:79]
	global_store_dwordx4 v[84:85], v[86:89], off
	global_store_dwordx2 v[90:91], v[80:81], off
	v_mul_f32_e32 v80, v87, v87
	v_mul_f32_e32 v81, v89, v89
	v_fmac_f32_e32 v80, v86, v86
	v_fmac_f32_e32 v81, v88, v88
	v_add_f32_e32 v90, v80, v81
	s_waitcnt vmcnt(17)
	v_mov_b64_e32 v[86:87], v[228:229]
	v_mov_b64_e32 v[88:89], v[230:231]
	v_pk_fma_f32 v[76:77], v[76:77], 0.5, v[88:89] op_sel_hi:[1,0,1]
	v_pk_fma_f32 v[74:75], v[74:75], 0.5, v[86:87] op_sel_hi:[1,0,1]
	global_store_dwordx4 v[84:85], v[74:77], off offset:64
	v_cvt_pk_bf16_f32 v80, v74, v75
	v_or_b32_e32 v86, 32, v78
	v_mul_f32_e32 v75, v75, v75
	v_mov_b32_e32 v87, v79
	v_fmac_f32_e32 v75, v74, v74
	v_mul_f32_e32 v74, v77, v77
	v_cvt_pk_bf16_f32 v81, v76, v77
	v_lshl_add_u64 v[86:87], s[14:15], 0, v[86:87]
	v_fmac_f32_e32 v74, v76, v76
	global_store_dwordx2 v[86:87], v[80:81], off
	v_add_f32_e32 v74, v75, v74
	v_add_f32_e32 v80, v90, v74
	s_waitcnt vmcnt(18)
	v_mov_b64_e32 v[74:75], v[232:233]
	v_mov_b64_e32 v[76:77], v[234:235]
	v_pk_fma_f32 v[72:73], v[72:73], 0.5, v[76:77] op_sel_hi:[1,0,1]
	v_pk_fma_f32 v[70:71], v[70:71], 0.5, v[74:75] op_sel_hi:[1,0,1]
	global_store_dwordx4 v[84:85], v[70:73], off offset:512
	v_cvt_pk_bf16_f32 v74, v70, v71
	v_or_b32_e32 v76, 0x100, v78
	v_mul_f32_e32 v71, v71, v71
	v_mov_b32_e32 v77, v79
	v_fmac_f32_e32 v71, v70, v70
	v_mul_f32_e32 v70, v73, v73
	v_cvt_pk_bf16_f32 v75, v72, v73
	v_lshl_add_u64 v[76:77], s[14:15], 0, v[76:77]
	v_fmac_f32_e32 v70, v72, v72
	global_store_dwordx2 v[76:77], v[74:75], off
	v_add_f32_e32 v70, v71, v70
	v_add_f32_e32 v74, v80, v70
	v_or_b32_e32 v78, 0x120, v78
	s_waitcnt vmcnt(19)
	v_mov_b64_e32 v[70:71], v[236:237]
	v_mov_b64_e32 v[72:73], v[238:239]
	v_pk_fma_f32 v[68:69], v[68:69], 0.5, v[72:73] op_sel_hi:[1,0,1]
	v_pk_fma_f32 v[66:67], v[66:67], 0.5, v[70:71] op_sel_hi:[1,0,1]
	global_store_dwordx4 v[84:85], v[66:69], off offset:576
	v_cvt_pk_bf16_f32 v70, v66, v67
	v_cvt_pk_bf16_f32 v71, v68, v69
	v_mul_f32_e32 v67, v67, v67
	v_fmac_f32_e32 v67, v66, v66
	v_mul_f32_e32 v66, v69, v69
	v_fmac_f32_e32 v66, v68, v68
	v_add_f32_e32 v66, v67, v66
	v_add_f32_e32 v66, v74, v66
	ds_bpermute_b32 v67, v162, v66
	v_lshl_add_u64 v[72:73], s[14:15], 0, v[78:79]
	global_store_dwordx2 v[72:73], v[70:71], off
	s_waitcnt lgkmcnt(0)
	v_add_f32_e32 v66, v66, v67
	ds_bpermute_b32 v67, v160, v66
	s_and_saveexec_b64 s[22:23], s[8:9]
	s_cbranch_execz .LBB0_321
	v_lshlrev_b64 v[68:69], 6, v[82:83]
	v_lshl_add_u64 v[68:69], s[66:67], 0, v[68:69]
	v_lshl_add_u64 v[68:69], s[20:21], 2, v[68:69]
	s_lshl_b32 s68, s39, 2
	v_lshl_add_u64 v[68:69], v[68:69], 0, s[68:69]
	s_waitcnt lgkmcnt(0)
	v_add_f32_e32 v66, v66, v67
	global_store_dword v[68:69], v66, off
.LBB0_321:
	s_or_b64 exec, exec, s[22:23]
	v_add_u32_e32 v66, 0x80, v138
	s_waitcnt lgkmcnt(0)
	v_ashrrev_i32_e32 v67, 31, v66
	v_lshlrev_b64 v[68:69], 10, v[66:67]
	v_lshl_add_u64 v[74:75], v[68:69], 0, v[136:137]
	v_lshl_add_u64 v[68:69], v[74:75], 2, s[4:5]
	s_mov_b64 s[22:23], 0x90000
	v_lshl_add_u64 v[206:207], v[204:205], 0, s[22:23]
	global_load_dwordx4 v[224:227], v[206:207], off
	global_load_dwordx4 v[228:231], v[206:207], off offset:64
	global_load_dwordx4 v[232:235], v[206:207], off offset:512
	global_load_dwordx4 v[236:239], v[206:207], off offset:576
	s_waitcnt vmcnt(16)
	v_mov_b64_e32 v[70:71], v[208:209]
	v_mov_b64_e32 v[72:73], v[210:211]
	v_pk_fma_f32 v[72:73], v[64:65], 0.5, v[72:73] op_sel_hi:[1,0,1]
	v_pk_fma_f32 v[70:71], v[62:63], 0.5, v[70:71] op_sel_hi:[1,0,1]
	v_lshlrev_b64 v[62:63], 1, v[74:75]
	v_cvt_pk_bf16_f32 v64, v70, v71
	v_cvt_pk_bf16_f32 v65, v72, v73
	v_lshl_add_u64 v[74:75], s[14:15], 0, v[62:63]
	global_store_dwordx4 v[68:69], v[70:73], off
	global_store_dwordx2 v[74:75], v[64:65], off
	v_mul_f32_e32 v64, v71, v71
	v_mul_f32_e32 v65, v73, v73
	v_fmac_f32_e32 v64, v70, v70
	v_fmac_f32_e32 v65, v72, v72
	v_add_f32_e32 v74, v64, v65
	s_waitcnt vmcnt(17)
	v_mov_b64_e32 v[70:71], v[212:213]
	v_mov_b64_e32 v[72:73], v[214:215]
	v_pk_fma_f32 v[60:61], v[60:61], 0.5, v[72:73] op_sel_hi:[1,0,1]
	v_pk_fma_f32 v[58:59], v[58:59], 0.5, v[70:71] op_sel_hi:[1,0,1]
	global_store_dwordx4 v[68:69], v[58:61], off offset:64
	v_cvt_pk_bf16_f32 v64, v58, v59
	v_or_b32_e32 v70, 32, v62
	v_mul_f32_e32 v59, v59, v59
	v_mov_b32_e32 v71, v63
	v_fmac_f32_e32 v59, v58, v58
	v_mul_f32_e32 v58, v61, v61
	v_cvt_pk_bf16_f32 v65, v60, v61
	v_lshl_add_u64 v[70:71], s[14:15], 0, v[70:71]
	v_fmac_f32_e32 v58, v60, v60
	global_store_dwordx2 v[70:71], v[64:65], off
	v_add_f32_e32 v58, v59, v58
	v_add_f32_e32 v64, v74, v58
	s_waitcnt vmcnt(18)
	v_mov_b64_e32 v[58:59], v[216:217]
	v_mov_b64_e32 v[60:61], v[218:219]
	v_pk_fma_f32 v[56:57], v[56:57], 0.5, v[60:61] op_sel_hi:[1,0,1]
	v_pk_fma_f32 v[54:55], v[54:55], 0.5, v[58:59] op_sel_hi:[1,0,1]
	global_store_dwordx4 v[68:69], v[54:57], off offset:512
	v_cvt_pk_bf16_f32 v58, v54, v55
	v_or_b32_e32 v60, 0x100, v62
	v_mul_f32_e32 v55, v55, v55
	v_mov_b32_e32 v61, v63
	v_fmac_f32_e32 v55, v54, v54
	v_mul_f32_e32 v54, v57, v57
	v_cvt_pk_bf16_f32 v59, v56, v57
	v_lshl_add_u64 v[60:61], s[14:15], 0, v[60:61]
	v_fmac_f32_e32 v54, v56, v56
	global_store_dwordx2 v[60:61], v[58:59], off
	v_add_f32_e32 v54, v55, v54
	v_add_f32_e32 v58, v64, v54
	v_or_b32_e32 v62, 0x120, v62
	s_waitcnt vmcnt(19)
	v_mov_b64_e32 v[54:55], v[220:221]
	v_mov_b64_e32 v[56:57], v[222:223]
	v_pk_fma_f32 v[52:53], v[52:53], 0.5, v[56:57] op_sel_hi:[1,0,1]
	v_pk_fma_f32 v[50:51], v[50:51], 0.5, v[54:55] op_sel_hi:[1,0,1]
	global_store_dwordx4 v[68:69], v[50:53], off offset:576
	v_cvt_pk_bf16_f32 v54, v50, v51
	v_cvt_pk_bf16_f32 v55, v52, v53
	v_mul_f32_e32 v51, v51, v51
	v_fmac_f32_e32 v51, v50, v50
	v_mul_f32_e32 v50, v53, v53
	v_fmac_f32_e32 v50, v52, v52
	v_add_f32_e32 v50, v51, v50
	v_add_f32_e32 v50, v58, v50
	ds_bpermute_b32 v51, v162, v50
	v_lshl_add_u64 v[56:57], s[14:15], 0, v[62:63]
	global_store_dwordx2 v[56:57], v[54:55], off
	s_waitcnt lgkmcnt(0)
	v_add_f32_e32 v50, v50, v51
	ds_bpermute_b32 v51, v160, v50
	s_and_saveexec_b64 s[22:23], s[8:9]
	s_cbranch_execz .LBB0_323
	v_lshlrev_b64 v[52:53], 6, v[66:67]
	v_lshl_add_u64 v[52:53], s[66:67], 0, v[52:53]
	v_lshl_add_u64 v[52:53], s[20:21], 2, v[52:53]
	s_lshl_b32 s68, s39, 2
	v_lshl_add_u64 v[52:53], v[52:53], 0, s[68:69]
	s_waitcnt lgkmcnt(0)
	v_add_f32_e32 v50, v50, v51
	global_store_dword v[52:53], v50, off
.LBB0_323:
	s_or_b64 exec, exec, s[22:23]
	v_add_u32_e32 v50, 0x90, v138
	s_waitcnt lgkmcnt(0)
	v_ashrrev_i32_e32 v51, 31, v50
	v_lshlrev_b64 v[52:53], 10, v[50:51]
	v_lshl_add_u64 v[58:59], v[52:53], 0, v[136:137]
	v_lshl_add_u64 v[52:53], v[58:59], 2, s[4:5]
	s_mov_b64 s[22:23], 0xa0000
	v_lshl_add_u64 v[206:207], v[204:205], 0, s[22:23]
	global_load_dwordx4 v[208:211], v[206:207], off
	global_load_dwordx4 v[212:215], v[206:207], off offset:64
	global_load_dwordx4 v[216:219], v[206:207], off offset:512
	global_load_dwordx4 v[220:223], v[206:207], off offset:576
	s_waitcnt vmcnt(16)
	v_mov_b64_e32 v[54:55], v[224:225]
	v_mov_b64_e32 v[56:57], v[226:227]
	v_pk_fma_f32 v[56:57], v[48:49], 0.5, v[56:57] op_sel_hi:[1,0,1]
	v_pk_fma_f32 v[54:55], v[46:47], 0.5, v[54:55] op_sel_hi:[1,0,1]
	v_lshlrev_b64 v[46:47], 1, v[58:59]
	v_cvt_pk_bf16_f32 v48, v54, v55
	v_cvt_pk_bf16_f32 v49, v56, v57
	v_lshl_add_u64 v[58:59], s[14:15], 0, v[46:47]
	global_store_dwordx4 v[52:53], v[54:57], off
	global_store_dwordx2 v[58:59], v[48:49], off
	v_mul_f32_e32 v48, v55, v55
	v_mul_f32_e32 v49, v57, v57
	v_fmac_f32_e32 v48, v54, v54
	v_fmac_f32_e32 v49, v56, v56
	v_add_f32_e32 v58, v48, v49
	s_waitcnt vmcnt(17)
	v_mov_b64_e32 v[54:55], v[228:229]
	v_mov_b64_e32 v[56:57], v[230:231]
	v_pk_fma_f32 v[44:45], v[44:45], 0.5, v[56:57] op_sel_hi:[1,0,1]
	v_pk_fma_f32 v[42:43], v[42:43], 0.5, v[54:55] op_sel_hi:[1,0,1]
	global_store_dwordx4 v[52:53], v[42:45], off offset:64
	v_cvt_pk_bf16_f32 v48, v42, v43
	v_or_b32_e32 v54, 32, v46
	v_mul_f32_e32 v43, v43, v43
	v_mov_b32_e32 v55, v47
	v_fmac_f32_e32 v43, v42, v42
	v_mul_f32_e32 v42, v45, v45
	v_cvt_pk_bf16_f32 v49, v44, v45
	v_lshl_add_u64 v[54:55], s[14:15], 0, v[54:55]
	v_fmac_f32_e32 v42, v44, v44
	global_store_dwordx2 v[54:55], v[48:49], off
	v_add_f32_e32 v42, v43, v42
	v_add_f32_e32 v48, v58, v42
	s_waitcnt vmcnt(18)
	v_mov_b64_e32 v[42:43], v[232:233]
	v_mov_b64_e32 v[44:45], v[234:235]
	v_pk_fma_f32 v[40:41], v[40:41], 0.5, v[44:45] op_sel_hi:[1,0,1]
	v_pk_fma_f32 v[38:39], v[38:39], 0.5, v[42:43] op_sel_hi:[1,0,1]
	global_store_dwordx4 v[52:53], v[38:41], off offset:512
	v_cvt_pk_bf16_f32 v42, v38, v39
	v_or_b32_e32 v44, 0x100, v46
	v_mul_f32_e32 v39, v39, v39
	v_mov_b32_e32 v45, v47
	v_fmac_f32_e32 v39, v38, v38
	v_mul_f32_e32 v38, v41, v41
	v_cvt_pk_bf16_f32 v43, v40, v41
	v_lshl_add_u64 v[44:45], s[14:15], 0, v[44:45]
	v_fmac_f32_e32 v38, v40, v40
	global_store_dwordx2 v[44:45], v[42:43], off
	v_add_f32_e32 v38, v39, v38
	v_add_f32_e32 v42, v48, v38
	v_or_b32_e32 v46, 0x120, v46
	s_waitcnt vmcnt(19)
	v_mov_b64_e32 v[38:39], v[236:237]
	v_mov_b64_e32 v[40:41], v[238:239]
	v_pk_fma_f32 v[36:37], v[36:37], 0.5, v[40:41] op_sel_hi:[1,0,1]
	v_pk_fma_f32 v[34:35], v[34:35], 0.5, v[38:39] op_sel_hi:[1,0,1]
	global_store_dwordx4 v[52:53], v[34:37], off offset:576
	v_cvt_pk_bf16_f32 v38, v34, v35
	v_cvt_pk_bf16_f32 v39, v36, v37
	v_mul_f32_e32 v35, v35, v35
	v_fmac_f32_e32 v35, v34, v34
	v_mul_f32_e32 v34, v37, v37
	v_fmac_f32_e32 v34, v36, v36
	v_add_f32_e32 v34, v35, v34
	v_add_f32_e32 v34, v42, v34
	ds_bpermute_b32 v35, v162, v34
	v_lshl_add_u64 v[40:41], s[14:15], 0, v[46:47]
	global_store_dwordx2 v[40:41], v[38:39], off
	s_waitcnt lgkmcnt(0)
	v_add_f32_e32 v34, v34, v35
	ds_bpermute_b32 v35, v160, v34
	s_and_saveexec_b64 s[22:23], s[8:9]
	s_cbranch_execz .LBB0_325
	v_lshlrev_b64 v[36:37], 6, v[50:51]
	v_lshl_add_u64 v[36:37], s[66:67], 0, v[36:37]
	v_lshl_add_u64 v[36:37], s[20:21], 2, v[36:37]
	s_lshl_b32 s68, s39, 2
	v_lshl_add_u64 v[36:37], v[36:37], 0, s[68:69]
	s_waitcnt lgkmcnt(0)
	v_add_f32_e32 v34, v34, v35
	global_store_dword v[36:37], v34, off
.LBB0_325:
	s_or_b64 exec, exec, s[22:23]
	v_add_u32_e32 v34, 0xa0, v138
	s_waitcnt lgkmcnt(0)
	v_ashrrev_i32_e32 v35, 31, v34
	v_lshlrev_b64 v[36:37], 10, v[34:35]
	v_lshl_add_u64 v[42:43], v[36:37], 0, v[136:137]
	v_lshl_add_u64 v[36:37], v[42:43], 2, s[4:5]
	s_mov_b64 s[22:23], 0xb0000
	v_lshl_add_u64 v[206:207], v[204:205], 0, s[22:23]
	global_load_dwordx4 v[224:227], v[206:207], off
	global_load_dwordx4 v[228:231], v[206:207], off offset:64
	global_load_dwordx4 v[232:235], v[206:207], off offset:512
	global_load_dwordx4 v[236:239], v[206:207], off offset:576
	s_waitcnt vmcnt(16)
	v_mov_b64_e32 v[38:39], v[208:209]
	v_mov_b64_e32 v[40:41], v[210:211]
	v_pk_fma_f32 v[40:41], v[32:33], 0.5, v[40:41] op_sel_hi:[1,0,1]
	v_pk_fma_f32 v[38:39], v[30:31], 0.5, v[38:39] op_sel_hi:[1,0,1]
	v_lshlrev_b64 v[30:31], 1, v[42:43]
	v_cvt_pk_bf16_f32 v32, v38, v39
	v_cvt_pk_bf16_f32 v33, v40, v41
	v_lshl_add_u64 v[42:43], s[14:15], 0, v[30:31]
	global_store_dwordx4 v[36:37], v[38:41], off
	global_store_dwordx2 v[42:43], v[32:33], off
	v_mul_f32_e32 v32, v39, v39
	v_mul_f32_e32 v33, v41, v41
	v_fmac_f32_e32 v32, v38, v38
	v_fmac_f32_e32 v33, v40, v40
	v_add_f32_e32 v42, v32, v33
	s_waitcnt vmcnt(17)
	v_mov_b64_e32 v[38:39], v[212:213]
	v_mov_b64_e32 v[40:41], v[214:215]
	v_pk_fma_f32 v[28:29], v[28:29], 0.5, v[40:41] op_sel_hi:[1,0,1]
	v_pk_fma_f32 v[26:27], v[26:27], 0.5, v[38:39] op_sel_hi:[1,0,1]
	global_store_dwordx4 v[36:37], v[26:29], off offset:64
	v_cvt_pk_bf16_f32 v32, v26, v27
	v_or_b32_e32 v38, 32, v30
	v_mul_f32_e32 v27, v27, v27
	v_mov_b32_e32 v39, v31
	v_fmac_f32_e32 v27, v26, v26
	v_mul_f32_e32 v26, v29, v29
	v_cvt_pk_bf16_f32 v33, v28, v29
	v_lshl_add_u64 v[38:39], s[14:15], 0, v[38:39]
	v_fmac_f32_e32 v26, v28, v28
	global_store_dwordx2 v[38:39], v[32:33], off
	v_add_f32_e32 v26, v27, v26
	v_add_f32_e32 v32, v42, v26
	s_waitcnt vmcnt(18)
	v_mov_b64_e32 v[26:27], v[216:217]
	v_mov_b64_e32 v[28:29], v[218:219]
	v_pk_fma_f32 v[24:25], v[24:25], 0.5, v[28:29] op_sel_hi:[1,0,1]
	v_pk_fma_f32 v[22:23], v[22:23], 0.5, v[26:27] op_sel_hi:[1,0,1]
	global_store_dwordx4 v[36:37], v[22:25], off offset:512
	v_cvt_pk_bf16_f32 v26, v22, v23
	v_or_b32_e32 v28, 0x100, v30
	v_mul_f32_e32 v23, v23, v23
	v_mov_b32_e32 v29, v31
	v_fmac_f32_e32 v23, v22, v22
	v_mul_f32_e32 v22, v25, v25
	v_cvt_pk_bf16_f32 v27, v24, v25
	v_lshl_add_u64 v[28:29], s[14:15], 0, v[28:29]
	v_fmac_f32_e32 v22, v24, v24
	global_store_dwordx2 v[28:29], v[26:27], off
	v_add_f32_e32 v22, v23, v22
	v_add_f32_e32 v26, v32, v22
	v_or_b32_e32 v30, 0x120, v30
	s_waitcnt vmcnt(19)
	v_mov_b64_e32 v[22:23], v[220:221]
	v_mov_b64_e32 v[24:25], v[222:223]
	v_pk_fma_f32 v[20:21], v[20:21], 0.5, v[24:25] op_sel_hi:[1,0,1]
	v_pk_fma_f32 v[18:19], v[18:19], 0.5, v[22:23] op_sel_hi:[1,0,1]
	global_store_dwordx4 v[36:37], v[18:21], off offset:576
	v_cvt_pk_bf16_f32 v22, v18, v19
	v_cvt_pk_bf16_f32 v23, v20, v21
	v_mul_f32_e32 v19, v19, v19
	v_fmac_f32_e32 v19, v18, v18
	v_mul_f32_e32 v18, v21, v21
	v_fmac_f32_e32 v18, v20, v20
	v_add_f32_e32 v18, v19, v18
	v_add_f32_e32 v18, v26, v18
	ds_bpermute_b32 v19, v162, v18
	v_lshl_add_u64 v[24:25], s[14:15], 0, v[30:31]
	global_store_dwordx2 v[24:25], v[22:23], off
	s_waitcnt lgkmcnt(0)
	v_add_f32_e32 v18, v18, v19
	ds_bpermute_b32 v19, v160, v18
	s_and_saveexec_b64 s[22:23], s[8:9]
	s_cbranch_execz .LBB0_327
	v_lshlrev_b64 v[20:21], 6, v[34:35]
	v_lshl_add_u64 v[20:21], s[66:67], 0, v[20:21]
	v_lshl_add_u64 v[20:21], s[20:21], 2, v[20:21]
	s_lshl_b32 s68, s39, 2
	v_lshl_add_u64 v[20:21], v[20:21], 0, s[68:69]
	s_waitcnt lgkmcnt(0)
	v_add_f32_e32 v18, v18, v19
	global_store_dword v[20:21], v18, off
.LBB0_327:
	s_or_b64 exec, exec, s[22:23]
	v_add_u32_e32 v18, 0xb0, v138
	s_waitcnt lgkmcnt(0)
	v_ashrrev_i32_e32 v19, 31, v18
	v_lshlrev_b64 v[20:21], 10, v[18:19]
	v_lshl_add_u64 v[26:27], v[20:21], 0, v[136:137]
	v_lshl_add_u64 v[20:21], v[26:27], 2, s[4:5]
	s_waitcnt vmcnt(12)
	v_mov_b64_e32 v[22:23], v[224:225]
	v_mov_b64_e32 v[24:25], v[226:227]
	v_pk_fma_f32 v[24:25], v[16:17], 0.5, v[24:25] op_sel_hi:[1,0,1]
	v_pk_fma_f32 v[22:23], v[14:15], 0.5, v[22:23] op_sel_hi:[1,0,1]
	v_lshlrev_b64 v[14:15], 1, v[26:27]
	v_cvt_pk_bf16_f32 v16, v22, v23
	v_cvt_pk_bf16_f32 v17, v24, v25
	v_lshl_add_u64 v[26:27], s[14:15], 0, v[14:15]
	global_store_dwordx4 v[20:21], v[22:25], off
	global_store_dwordx2 v[26:27], v[16:17], off
	v_mul_f32_e32 v16, v23, v23
	v_mul_f32_e32 v17, v25, v25
	v_fmac_f32_e32 v16, v22, v22
	v_fmac_f32_e32 v17, v24, v24
	v_add_f32_e32 v26, v16, v17
	s_waitcnt vmcnt(13)
	v_mov_b64_e32 v[22:23], v[228:229]
	v_mov_b64_e32 v[24:25], v[230:231]
	v_pk_fma_f32 v[12:13], v[12:13], 0.5, v[24:25] op_sel_hi:[1,0,1]
	v_pk_fma_f32 v[10:11], v[10:11], 0.5, v[22:23] op_sel_hi:[1,0,1]
	global_store_dwordx4 v[20:21], v[10:13], off offset:64
	v_cvt_pk_bf16_f32 v16, v10, v11
	v_or_b32_e32 v22, 32, v14
	v_mul_f32_e32 v11, v11, v11
	v_mov_b32_e32 v23, v15
	v_fmac_f32_e32 v11, v10, v10
	v_mul_f32_e32 v10, v13, v13
	v_cvt_pk_bf16_f32 v17, v12, v13
	v_lshl_add_u64 v[22:23], s[14:15], 0, v[22:23]
	v_fmac_f32_e32 v10, v12, v12
	global_store_dwordx2 v[22:23], v[16:17], off
	v_add_f32_e32 v10, v11, v10
	v_add_f32_e32 v16, v26, v10
	s_waitcnt vmcnt(14)
	v_mov_b64_e32 v[10:11], v[232:233]
	v_mov_b64_e32 v[12:13], v[234:235]
	v_pk_fma_f32 v[8:9], v[8:9], 0.5, v[12:13] op_sel_hi:[1,0,1]
	v_pk_fma_f32 v[6:7], v[6:7], 0.5, v[10:11] op_sel_hi:[1,0,1]
	global_store_dwordx4 v[20:21], v[6:9], off offset:512
	v_cvt_pk_bf16_f32 v10, v6, v7
	v_or_b32_e32 v12, 0x100, v14
	v_mul_f32_e32 v7, v7, v7
	v_mov_b32_e32 v13, v15
	v_fmac_f32_e32 v7, v6, v6
	v_mul_f32_e32 v6, v9, v9
	v_cvt_pk_bf16_f32 v11, v8, v9
	v_lshl_add_u64 v[12:13], s[14:15], 0, v[12:13]
	v_fmac_f32_e32 v6, v8, v8
	global_store_dwordx2 v[12:13], v[10:11], off
	v_add_f32_e32 v6, v7, v6
	v_add_f32_e32 v10, v16, v6
	v_or_b32_e32 v14, 0x120, v14
	s_waitcnt vmcnt(15)
	v_mov_b64_e32 v[6:7], v[236:237]
	v_mov_b64_e32 v[8:9], v[238:239]
	v_pk_fma_f32 v[4:5], v[4:5], 0.5, v[8:9] op_sel_hi:[1,0,1]
	v_pk_fma_f32 v[2:3], v[2:3], 0.5, v[6:7] op_sel_hi:[1,0,1]
	global_store_dwordx4 v[20:21], v[2:5], off offset:576
	v_cvt_pk_bf16_f32 v6, v2, v3
	v_cvt_pk_bf16_f32 v7, v4, v5
	v_mul_f32_e32 v3, v3, v3
	v_fmac_f32_e32 v3, v2, v2
	v_mul_f32_e32 v2, v5, v5
	v_fmac_f32_e32 v2, v4, v4
	v_add_f32_e32 v2, v3, v2
	v_add_f32_e32 v2, v10, v2
	ds_bpermute_b32 v3, v162, v2
	v_lshl_add_u64 v[8:9], s[14:15], 0, v[14:15]
	global_store_dwordx2 v[8:9], v[6:7], off
	s_waitcnt lgkmcnt(0)
	v_add_f32_e32 v2, v2, v3
	ds_bpermute_b32 v3, v160, v2
	s_and_saveexec_b64 s[22:23], s[8:9]
	s_cbranch_execz .LBB0_329
	v_lshlrev_b64 v[4:5], 6, v[18:19]
	v_lshl_add_u64 v[4:5], s[66:67], 0, v[4:5]
	v_lshl_add_u64 v[4:5], s[20:21], 2, v[4:5]
	s_lshl_b32 s68, s39, 2
	v_lshl_add_u64 v[4:5], v[4:5], 0, s[68:69]
	s_waitcnt lgkmcnt(0)
	v_add_f32_e32 v2, v2, v3
	global_store_dword v[4:5], v2, off
